# s6 out-proj epilogue: residual loads batched (rolling 12 in flight), ln_g/ln_b loads deferred, LN stat loads issued together
# speedup vs baseline: 1.0020x; 1.0020x over previous
.LBB0_331:
	s_add_i32 s2, s70, 5
	v_readlane_b32 s24, v254, 1
	s_cmp_gt_u32 s2, 12
	v_readlane_b32 s25, v254, 2
	s_cselect_b64 s[38:39], -1, 0
	s_cmp_lt_u32 s2, 13
	v_readlane_b32 s30, v254, 7
	v_readlane_b32 s31, v254, 8
	s_mov_b64 s[24:25], s[64:65]
	s_cselect_b32 s37, s45, s31
	s_cselect_b32 s36, s44, s30
	s_lshl_b32 s2, s24, 10
	s_ashr_i32 s3, s2, 31
	v_readlane_b32 s26, v254, 3
	s_lshl_b64 s[2:3], s[2:3], 2
	v_readlane_b32 s27, v254, 4
	s_add_u32 s4, s26, s2
	v_readlane_b32 s28, v254, 5
	s_addc_u32 s5, s27, s3
	v_readlane_b32 s29, v254, 6
	s_add_u32 s2, s28, s2
	v_and_b32_e32 v163, 64, v210
	s_addc_u32 s3, s29, s3
	s_lshl_b32 s6, s21, 5
	s_lshl_b32 s7, s9, 8
	v_xor_b32_e32 v162, 16, v210
	v_add_u32_e32 v163, 64, v163
	s_or_b32 s6, s7, s6
	v_lshrrev_b32_e32 v0, 2, v10
	v_cmp_lt_i32_e32 vcc, v162, v163
	v_and_or_b32 v160, v0, 12, s6
	v_ashrrev_i32_e32 v161, 31, v160
	v_cndmask_b32_e32 v162, v210, v162, vcc
	v_lshlrev_b32_e32 v194, 2, v162
	v_xor_b32_e32 v162, 32, v210
	v_lshlrev_b64 v[164:165], 2, v[160:161]
	v_cmp_lt_i32_e32 vcc, v162, v163
	s_lshl_b32 s5, s82, 8
	v_cndmask_b32_e32 v162, v210, v162, vcc
	v_lshlrev_b32_e32 v193, 2, v162
	v_add_u32_e32 v162, s5, v192
	v_ashrrev_i32_e32 v163, 31, v162
	v_lshlrev_b64 v[166:167], 12, v[162:163]
	v_lshl_add_u64 v[166:167], s[36:37], 0, v[166:167]
	v_lshl_add_u64 v[190:191], v[166:167], 0, v[164:165]
	v_and_b32_e32 v176, 63, v10
	s_barrier
	v_add_u32_e32 v252, s5, v192
	v_lshlrev_b32_e32 v252, 12, v252
	v_lshl_add_u32 v252, v160, 2, v252
	global_load_dwordx4 v[0:3], v252, s[36:37]
	global_load_dwordx4 v[4:7], v252, s[36:37] offset:64
	global_load_dwordx4 v[8:11], v252, s[36:37] offset:512
	global_load_dwordx4 v[12:15], v252, s[36:37] offset:576
	v_add_u32_e32 v253, 0x10000, v252
	global_load_dwordx4 v[16:19], v253, s[36:37]
	global_load_dwordx4 v[20:23], v253, s[36:37] offset:64
	global_load_dwordx4 v[24:27], v253, s[36:37] offset:512
	global_load_dwordx4 v[28:31], v253, s[36:37] offset:576
	v_add_u32_e32 v253, 0x20000, v252
	global_load_dwordx4 v[244:247], v253, s[36:37]
	global_load_dwordx4 v[248:251], v253, s[36:37] offset:64
	global_load_dwordx4 v[178:181], v253, s[36:37] offset:512
	global_load_dwordx4 v[182:185], v253, s[36:37] offset:576
	s_mov_b32 s2, 0x3fb504f3
	v_cmp_gt_u32_e32 vcc, 16, v176
	s_lshl_b32 s4, s21, 3
	s_waitcnt vmcnt(8)
	v_pk_fma_f32 v[158:159], v[2:3], s[2:3], v[158:159] op_sel_hi:[1,0,1]
	v_pk_fma_f32 v[154:155], v[6:7], s[2:3], v[154:155] op_sel_hi:[1,0,1]
	v_pk_fma_f32 v[152:153], v[4:5], s[2:3], v[152:153] op_sel_hi:[1,0,1]
	v_pk_fma_f32 v[156:157], v[0:1], s[2:3], v[156:157] op_sel_hi:[1,0,1]
	v_mul_f32_e32 v169, v158, v158
	v_mul_f32_e32 v168, v154, v154
	v_add_f32_e32 v164, v156, v157
	v_add_f32_e32 v166, v158, v159
	v_mul_f32_e32 v173, v156, v156
	v_mul_f32_e32 v175, v157, v157
	v_mul_f32_e32 v171, v159, v159
	v_mul_f32_e32 v165, v152, v152
	v_mul_f32_e32 v167, v153, v153
	v_pk_fma_f32 v[196:197], v[154:155], v[154:155], v[168:169] op_sel_hi:[1,1,0]
	v_mov_b32_e32 v172, v152
	v_mov_b32_e32 v174, v153
	v_mov_b32_e32 v168, v154
	v_mov_b32_e32 v170, v155
	v_pk_add_f32 v[172:173], v[172:173], v[174:175]
	v_pk_add_f32 v[168:169], v[168:169], v[170:171]
	v_pk_add_f32 v[164:165], v[164:165], v[166:167]
	v_mov_b32_e32 v196, v177
	v_pk_add_f32 v[168:169], v[172:173], v[168:169]
	v_pk_add_f32 v[164:165], v[164:165], v[196:197]
	v_pk_fma_f32 v[150:151], v[10:11], s[2:3], v[150:151] op_sel_hi:[1,0,1]
	v_pk_fma_f32 v[148:149], v[8:9], s[2:3], v[148:149] op_sel_hi:[1,0,1]
	v_mul_f32_e32 v199, v148, v148
	v_mul_f32_e32 v201, v149, v149
	v_mul_f32_e32 v203, v150, v150
	v_mul_f32_e32 v205, v151, v151
	v_mov_b32_e32 v198, v148
	v_mov_b32_e32 v200, v149
	v_mov_b32_e32 v202, v150
	v_mov_b32_e32 v204, v151
	v_pk_add_f32 v[164:165], v[168:169], v[164:165]
	v_pk_add_f32 v[166:167], v[198:199], v[200:201]
	v_pk_add_f32 v[168:169], v[202:203], v[204:205]
	v_pk_fma_f32 v[146:147], v[14:15], s[2:3], v[146:147] op_sel_hi:[1,0,1]
	v_pk_fma_f32 v[144:145], v[12:13], s[2:3], v[144:145] op_sel_hi:[1,0,1]
	v_add_u32_e32 v253, 0x30000, v252
	global_load_dwordx4 v[0:3], v253, s[36:37]
	global_load_dwordx4 v[4:7], v253, s[36:37] offset:64
	global_load_dwordx4 v[8:11], v253, s[36:37] offset:512
	global_load_dwordx4 v[12:15], v253, s[36:37] offset:576
	v_mul_f32_e32 v191, v146, v146
	v_mul_f32_e32 v187, v144, v144
	v_mul_f32_e32 v189, v145, v145
	v_mul_f32_e32 v215, v147, v147
	v_pk_add_f32 v[166:167], v[166:167], v[168:169]
	v_mov_b32_e32 v186, v144
	v_mov_b32_e32 v188, v145
	v_mov_b32_e32 v190, v146
	v_mov_b32_e32 v214, v147
	v_pk_add_f32 v[164:165], v[164:165], v[166:167]
	v_pk_add_f32 v[166:167], v[186:187], v[188:189]
	v_pk_add_f32 v[168:169], v[190:191], v[214:215]
	s_nop 0
	v_pk_add_f32 v[166:167], v[166:167], v[168:169]
	s_nop 0
	v_pk_add_f32 v[164:165], v[164:165], v[166:167]
	ds_bpermute_b32 v166, v194, v164
	ds_bpermute_b32 v167, v194, v165
	s_waitcnt lgkmcnt(0)
	v_pk_add_f32 v[164:165], v[164:165], v[166:167]
	ds_bpermute_b32 v166, v193, v164
	ds_bpermute_b32 v167, v193, v165
	s_and_saveexec_b64 s[2:3], vcc
	v_readlane_b32 s60, v255, 42
	v_readlane_b32 s62, v255, 44
	v_readlane_b32 s64, v255, 46
	v_readlane_b32 s74, v255, 48
	v_readlane_b32 s34, v255, 38
	v_readlane_b32 s42, v255, 41
	v_readlane_b32 s61, v255, 43
	v_readlane_b32 s63, v255, 45
	v_readlane_b32 s65, v255, 47
	v_readlane_b32 s75, v255, 49
	v_readlane_b32 s43, v255, 50
	v_readlane_b32 s35, v255, 39
	s_cbranch_execz .LBB0_333
	v_lshl_or_b32 v168, v192, 5, s4
	s_waitcnt lgkmcnt(0)
	v_pk_add_f32 v[164:165], v[164:165], v[166:167]
	ds_write_b64 v168, v[164:165]
.LBB0_333:
	s_or_b64 exec, exec, s[2:3]
	v_or_b32_e32 v196, 16, v192
	v_add_u32_e32 v164, s5, v196
	v_ashrrev_i32_e32 v165, 31, v164
	s_waitcnt lgkmcnt(0)
	v_lshlrev_b64 v[166:167], 12, v[164:165]
	v_lshl_add_u64 v[166:167], s[36:37], 0, v[166:167]
	v_lshl_add_u64 v[170:171], v[160:161], 2, v[166:167]
	s_mov_b32 s2, 0x3fb504f3
	s_waitcnt vmcnt(8)
	v_pk_fma_f32 v[142:143], v[18:19], s[2:3], v[142:143] op_sel_hi:[1,0,1]
	v_pk_fma_f32 v[140:141], v[16:17], s[2:3], v[140:141] op_sel_hi:[1,0,1]
	v_add_f32_e32 v172, v140, v141
	v_add_f32_e32 v174, v142, v143
	v_mul_f32_e32 v187, v140, v140
	v_mul_f32_e32 v189, v141, v141
	v_mul_f32_e32 v191, v142, v142
	v_mul_f32_e32 v199, v143, v143
	v_pk_fma_f32 v[138:139], v[22:23], s[2:3], v[138:139] op_sel_hi:[1,0,1]
	v_pk_fma_f32 v[136:137], v[20:21], s[2:3], v[136:137] op_sel_hi:[1,0,1]
	v_mul_f32_e32 v166, v138, v138
	v_pk_fma_f32 v[200:201], v[138:139], v[138:139], v[166:167] op_sel_hi:[1,1,0]
	v_mul_f32_e32 v173, v136, v136
	v_mul_f32_e32 v175, v137, v137
	v_mov_b32_e32 v186, v136
	v_mov_b32_e32 v188, v137
	v_mov_b32_e32 v190, v138
	v_mov_b32_e32 v198, v139
	v_pk_add_f32 v[186:187], v[186:187], v[188:189]
	v_pk_add_f32 v[188:189], v[190:191], v[198:199]
	v_pk_add_f32 v[172:173], v[172:173], v[174:175]
	v_mov_b32_e32 v200, v177
	v_pk_add_f32 v[186:187], v[186:187], v[188:189]
	v_pk_add_f32 v[172:173], v[172:173], v[200:201]
	v_pk_fma_f32 v[134:135], v[26:27], s[2:3], v[134:135] op_sel_hi:[1,0,1]
	v_pk_fma_f32 v[132:133], v[24:25], s[2:3], v[132:133] op_sel_hi:[1,0,1]
	v_mul_f32_e32 v203, v132, v132
	v_mul_f32_e32 v205, v133, v133
	v_mul_f32_e32 v215, v134, v134
	v_mul_f32_e32 v221, v135, v135
	v_mov_b32_e32 v202, v132
	v_mov_b32_e32 v204, v133
	v_mov_b32_e32 v214, v134
	v_mov_b32_e32 v220, v135
	v_pk_add_f32 v[172:173], v[186:187], v[172:173]
	v_pk_add_f32 v[174:175], v[202:203], v[204:205]
	v_pk_add_f32 v[186:187], v[214:215], v[220:221]
	v_pk_fma_f32 v[130:131], v[30:31], s[2:3], v[130:131] op_sel_hi:[1,0,1]
	v_pk_fma_f32 v[128:129], v[28:29], s[2:3], v[128:129] op_sel_hi:[1,0,1]
	v_add_u32_e32 v253, 0x80000, v252
	global_load_dwordx4 v[16:19], v253, s[36:37]
	global_load_dwordx4 v[20:23], v253, s[36:37] offset:64
	global_load_dwordx4 v[24:27], v253, s[36:37] offset:512
	global_load_dwordx4 v[28:31], v253, s[36:37] offset:576
	v_mul_f32_e32 v171, v130, v130
	v_mul_f32_e32 v167, v128, v128
	v_mul_f32_e32 v169, v129, v129
	v_mul_f32_e32 v223, v131, v131
	v_mov_b32_e32 v166, v128
	v_mov_b32_e32 v168, v129
	v_mov_b32_e32 v170, v130
	v_mov_b32_e32 v222, v131
	v_pk_add_f32 v[174:175], v[174:175], v[186:187]
	v_pk_add_f32 v[166:167], v[166:167], v[168:169]
	v_pk_add_f32 v[168:169], v[170:171], v[222:223]
	v_pk_add_f32 v[172:173], v[172:173], v[174:175]
	v_pk_add_f32 v[166:167], v[166:167], v[168:169]
	s_nop 0
	v_pk_add_f32 v[166:167], v[172:173], v[166:167]
	ds_bpermute_b32 v168, v194, v166
	ds_bpermute_b32 v169, v194, v167
	s_waitcnt lgkmcnt(0)
	v_pk_add_f32 v[166:167], v[166:167], v[168:169]
	ds_bpermute_b32 v168, v193, v166
	ds_bpermute_b32 v169, v193, v167
	s_and_saveexec_b64 s[2:3], vcc
	v_readlane_b32 s35, v255, 40
	s_movk_i32 s26, 0x1ff
	s_cbranch_execz .LBB0_335
	v_lshl_or_b32 v170, v196, 5, s4
	s_waitcnt lgkmcnt(0)
	v_pk_add_f32 v[166:167], v[166:167], v[168:169]
	ds_write_b64 v170, v[166:167]
.LBB0_335:
	s_or_b64 exec, exec, s[2:3]
	v_or_b32_e32 v197, 32, v192
	v_add_u32_e32 v166, s5, v197
	v_ashrrev_i32_e32 v167, 31, v166
	s_waitcnt lgkmcnt(0)
	v_lshlrev_b64 v[168:169], 12, v[166:167]
	v_lshl_add_u64 v[168:169], s[36:37], 0, v[168:169]
	v_lshl_add_u64 v[172:173], v[160:161], 2, v[168:169]
	s_mov_b32 s2, 0x3fb504f3
	s_waitcnt vmcnt(8)
	v_pk_fma_f32 v[126:127], v[246:247], s[2:3], v[126:127] op_sel_hi:[1,0,1]
	v_pk_fma_f32 v[124:125], v[244:245], s[2:3], v[124:125] op_sel_hi:[1,0,1]
	v_add_f32_e32 v174, v124, v125
	v_add_f32_e32 v186, v126, v127
	v_mul_f32_e32 v189, v124, v124
	v_mul_f32_e32 v191, v125, v125
	v_mul_f32_e32 v199, v126, v126
	v_mul_f32_e32 v201, v127, v127
	v_pk_fma_f32 v[122:123], v[250:251], s[2:3], v[122:123] op_sel_hi:[1,0,1]
	v_pk_fma_f32 v[120:121], v[248:249], s[2:3], v[120:121] op_sel_hi:[1,0,1]
	v_mul_f32_e32 v168, v122, v122
	v_pk_fma_f32 v[202:203], v[122:123], v[122:123], v[168:169] op_sel_hi:[1,1,0]
	v_mul_f32_e32 v175, v120, v120
	v_mul_f32_e32 v187, v121, v121
	v_mov_b32_e32 v188, v120
	v_mov_b32_e32 v190, v121
	v_mov_b32_e32 v198, v122
	v_mov_b32_e32 v200, v123
	v_pk_add_f32 v[188:189], v[188:189], v[190:191]
	v_pk_add_f32 v[190:191], v[198:199], v[200:201]
	v_pk_add_f32 v[174:175], v[174:175], v[186:187]
	v_mov_b32_e32 v202, v177
	v_pk_add_f32 v[188:189], v[188:189], v[190:191]
	v_pk_add_f32 v[174:175], v[174:175], v[202:203]
	v_pk_fma_f32 v[118:119], v[180:181], s[2:3], v[118:119] op_sel_hi:[1,0,1]
	v_pk_fma_f32 v[116:117], v[178:179], s[2:3], v[116:117] op_sel_hi:[1,0,1]
	v_mul_f32_e32 v205, v116, v116
	v_mul_f32_e32 v215, v117, v117
	v_mul_f32_e32 v221, v118, v118
	v_mul_f32_e32 v223, v119, v119
	v_mov_b32_e32 v204, v116
	v_mov_b32_e32 v214, v117
	v_mov_b32_e32 v220, v118
	v_mov_b32_e32 v222, v119
	v_pk_add_f32 v[174:175], v[188:189], v[174:175]
	v_pk_add_f32 v[186:187], v[204:205], v[214:215]
	v_pk_add_f32 v[188:189], v[220:221], v[222:223]
	v_pk_fma_f32 v[114:115], v[184:185], s[2:3], v[114:115] op_sel_hi:[1,0,1]
	v_pk_fma_f32 v[112:113], v[182:183], s[2:3], v[112:113] op_sel_hi:[1,0,1]
	v_add_u32_e32 v253, 0x90000, v252
	global_load_dwordx4 v[244:247], v253, s[36:37]
	global_load_dwordx4 v[248:251], v253, s[36:37] offset:64
	global_load_dwordx4 v[178:181], v253, s[36:37] offset:512
	global_load_dwordx4 v[182:185], v253, s[36:37] offset:576
	v_mul_f32_e32 v173, v114, v114
	v_mul_f32_e32 v169, v112, v112
	v_mul_f32_e32 v171, v113, v113
	v_mul_f32_e32 v225, v115, v115
	v_mov_b32_e32 v168, v112
	v_mov_b32_e32 v170, v113
	v_mov_b32_e32 v172, v114
	v_mov_b32_e32 v224, v115
	v_pk_add_f32 v[186:187], v[186:187], v[188:189]
	v_pk_add_f32 v[168:169], v[168:169], v[170:171]
	v_pk_add_f32 v[170:171], v[172:173], v[224:225]
	v_pk_add_f32 v[174:175], v[174:175], v[186:187]
	v_pk_add_f32 v[168:169], v[168:169], v[170:171]
	s_nop 0
	v_pk_add_f32 v[168:169], v[174:175], v[168:169]
	ds_bpermute_b32 v170, v194, v168
	ds_bpermute_b32 v171, v194, v169
	s_waitcnt lgkmcnt(0)
	v_pk_add_f32 v[168:169], v[168:169], v[170:171]
	ds_bpermute_b32 v170, v193, v168
	ds_bpermute_b32 v171, v193, v169
	s_and_saveexec_b64 s[2:3], vcc
	s_cbranch_execz .LBB0_337
	v_lshl_or_b32 v172, v197, 5, s4
	s_waitcnt lgkmcnt(0)
	v_pk_add_f32 v[168:169], v[168:169], v[170:171]
	ds_write_b64 v172, v[168:169]
.LBB0_337:
	s_or_b64 exec, exec, s[2:3]
	v_or_b32_e32 v198, 48, v192
	v_add_u32_e32 v168, s5, v198
	v_ashrrev_i32_e32 v169, 31, v168
	s_waitcnt lgkmcnt(0)
	v_lshlrev_b64 v[170:171], 12, v[168:169]
	v_lshl_add_u64 v[170:171], s[36:37], 0, v[170:171]
	v_lshl_add_u64 v[174:175], v[160:161], 2, v[170:171]
	s_mov_b32 s2, 0x3fb504f3
	s_waitcnt vmcnt(8)
	v_pk_fma_f32 v[110:111], v[2:3], s[2:3], v[110:111] op_sel_hi:[1,0,1]
	v_pk_fma_f32 v[108:109], v[0:1], s[2:3], v[108:109] op_sel_hi:[1,0,1]
	v_add_f32_e32 v186, v108, v109
	v_add_f32_e32 v188, v110, v111
	v_mul_f32_e32 v191, v108, v108
	v_mul_f32_e32 v201, v109, v109
	v_mul_f32_e32 v203, v110, v110
	v_mul_f32_e32 v205, v111, v111
	v_pk_fma_f32 v[106:107], v[6:7], s[2:3], v[106:107] op_sel_hi:[1,0,1]
	v_pk_fma_f32 v[104:105], v[4:5], s[2:3], v[104:105] op_sel_hi:[1,0,1]
	v_mul_f32_e32 v170, v106, v106
	v_pk_fma_f32 v[214:215], v[106:107], v[106:107], v[170:171] op_sel_hi:[1,1,0]
	v_mul_f32_e32 v187, v104, v104
	v_mul_f32_e32 v189, v105, v105
	v_mov_b32_e32 v190, v104
	v_mov_b32_e32 v200, v105
	v_mov_b32_e32 v202, v106
	v_mov_b32_e32 v204, v107
	v_pk_add_f32 v[190:191], v[190:191], v[200:201]
	v_pk_add_f32 v[200:201], v[202:203], v[204:205]
	v_pk_add_f32 v[186:187], v[186:187], v[188:189]
	v_mov_b32_e32 v214, v177
	v_pk_add_f32 v[190:191], v[190:191], v[200:201]
	v_pk_add_f32 v[186:187], v[186:187], v[214:215]
	v_pk_fma_f32 v[102:103], v[10:11], s[2:3], v[102:103] op_sel_hi:[1,0,1]
	v_pk_fma_f32 v[100:101], v[8:9], s[2:3], v[100:101] op_sel_hi:[1,0,1]
	v_mul_f32_e32 v221, v100, v100
	v_mul_f32_e32 v223, v101, v101
	v_mul_f32_e32 v225, v102, v102
	v_mul_f32_e32 v227, v103, v103
	v_mov_b32_e32 v220, v100
	v_mov_b32_e32 v222, v101
	v_mov_b32_e32 v224, v102
	v_mov_b32_e32 v226, v103
	v_pk_add_f32 v[186:187], v[190:191], v[186:187]
	v_pk_add_f32 v[188:189], v[220:221], v[222:223]
	v_pk_add_f32 v[190:191], v[224:225], v[226:227]
	v_pk_fma_f32 v[98:99], v[14:15], s[2:3], v[98:99] op_sel_hi:[1,0,1]
	v_pk_fma_f32 v[96:97], v[12:13], s[2:3], v[96:97] op_sel_hi:[1,0,1]
	v_add_u32_e32 v253, 0xa0000, v252
	global_load_dwordx4 v[0:3], v253, s[36:37]
	global_load_dwordx4 v[4:7], v253, s[36:37] offset:64
	global_load_dwordx4 v[8:11], v253, s[36:37] offset:512
	global_load_dwordx4 v[12:15], v253, s[36:37] offset:576
	v_mul_f32_e32 v175, v98, v98
	v_mul_f32_e32 v171, v96, v96
	v_mul_f32_e32 v173, v97, v97
	v_mul_f32_e32 v229, v99, v99
	v_mov_b32_e32 v170, v96
	v_mov_b32_e32 v172, v97
	v_mov_b32_e32 v174, v98
	v_mov_b32_e32 v228, v99
	v_pk_add_f32 v[188:189], v[188:189], v[190:191]
	v_pk_add_f32 v[170:171], v[170:171], v[172:173]
	v_pk_add_f32 v[172:173], v[174:175], v[228:229]
	v_pk_add_f32 v[186:187], v[186:187], v[188:189]
	v_pk_add_f32 v[170:171], v[170:171], v[172:173]
	s_nop 0
	v_pk_add_f32 v[170:171], v[186:187], v[170:171]
	ds_bpermute_b32 v172, v194, v170
	ds_bpermute_b32 v173, v194, v171
	s_waitcnt lgkmcnt(0)
	v_pk_add_f32 v[170:171], v[170:171], v[172:173]
	ds_bpermute_b32 v172, v193, v170
	ds_bpermute_b32 v173, v193, v171
	s_and_saveexec_b64 s[2:3], vcc
	s_cbranch_execz .LBB0_339
	v_lshl_or_b32 v174, v198, 5, s4
	s_waitcnt lgkmcnt(0)
	v_pk_add_f32 v[170:171], v[170:171], v[172:173]
	ds_write_b64 v174, v[170:171]
.LBB0_339:
	s_or_b64 exec, exec, s[2:3]
	v_add_u32_e32 v199, 0x80, v192
	v_add_u32_e32 v170, s5, v199
	v_ashrrev_i32_e32 v171, 31, v170
	s_waitcnt lgkmcnt(0)
	v_lshlrev_b64 v[172:173], 12, v[170:171]
	v_lshl_add_u64 v[172:173], s[36:37], 0, v[172:173]
	v_lshl_add_u64 v[186:187], v[160:161], 2, v[172:173]
	s_mov_b32 s2, 0x3fb504f3
	s_waitcnt vmcnt(8)
	v_pk_fma_f32 v[94:95], v[18:19], s[2:3], v[94:95] op_sel_hi:[1,0,1]
	v_pk_fma_f32 v[92:93], v[16:17], s[2:3], v[92:93] op_sel_hi:[1,0,1]
	v_add_f32_e32 v188, v92, v93
	v_add_f32_e32 v190, v94, v95
	v_mul_f32_e32 v201, v92, v92
	v_mul_f32_e32 v203, v93, v93
	v_mul_f32_e32 v205, v94, v94
	v_mul_f32_e32 v215, v95, v95
	v_pk_fma_f32 v[90:91], v[22:23], s[2:3], v[90:91] op_sel_hi:[1,0,1]
	v_pk_fma_f32 v[88:89], v[20:21], s[2:3], v[88:89] op_sel_hi:[1,0,1]
	v_mul_f32_e32 v172, v90, v90
	v_pk_fma_f32 v[220:221], v[90:91], v[90:91], v[172:173] op_sel_hi:[1,1,0]
	v_mul_f32_e32 v189, v88, v88
	v_mul_f32_e32 v191, v89, v89
	v_mov_b32_e32 v200, v88
	v_mov_b32_e32 v202, v89
	v_mov_b32_e32 v204, v90
	v_mov_b32_e32 v214, v91
	v_pk_add_f32 v[200:201], v[200:201], v[202:203]
	v_pk_add_f32 v[202:203], v[204:205], v[214:215]
	v_pk_add_f32 v[188:189], v[188:189], v[190:191]
	v_mov_b32_e32 v220, v177
	v_pk_add_f32 v[200:201], v[200:201], v[202:203]
	v_pk_add_f32 v[188:189], v[188:189], v[220:221]
	v_pk_fma_f32 v[86:87], v[26:27], s[2:3], v[86:87] op_sel_hi:[1,0,1]
	v_pk_fma_f32 v[84:85], v[24:25], s[2:3], v[84:85] op_sel_hi:[1,0,1]
	v_mul_f32_e32 v223, v84, v84
	v_mul_f32_e32 v225, v85, v85
	v_mul_f32_e32 v227, v86, v86
	v_mul_f32_e32 v229, v87, v87
	v_mov_b32_e32 v222, v84
	v_mov_b32_e32 v224, v85
	v_mov_b32_e32 v226, v86
	v_mov_b32_e32 v228, v87
	v_pk_add_f32 v[188:189], v[200:201], v[188:189]
	v_pk_add_f32 v[190:191], v[222:223], v[224:225]
	v_pk_add_f32 v[200:201], v[226:227], v[228:229]
	v_pk_fma_f32 v[82:83], v[30:31], s[2:3], v[82:83] op_sel_hi:[1,0,1]
	v_pk_fma_f32 v[80:81], v[28:29], s[2:3], v[80:81] op_sel_hi:[1,0,1]
	v_add_u32_e32 v253, 0xb0000, v252
	global_load_dwordx4 v[16:19], v253, s[36:37]
	global_load_dwordx4 v[20:23], v253, s[36:37] offset:64
	global_load_dwordx4 v[24:27], v253, s[36:37] offset:512
	global_load_dwordx4 v[28:31], v253, s[36:37] offset:576
	v_mul_f32_e32 v187, v82, v82
	v_mul_f32_e32 v173, v80, v80
	v_mul_f32_e32 v175, v81, v81
	v_mul_f32_e32 v231, v83, v83
	v_mov_b32_e32 v172, v80
	v_mov_b32_e32 v174, v81
	v_mov_b32_e32 v186, v82
	v_mov_b32_e32 v230, v83
	v_pk_add_f32 v[190:191], v[190:191], v[200:201]
	v_pk_add_f32 v[172:173], v[172:173], v[174:175]
	v_pk_add_f32 v[174:175], v[186:187], v[230:231]
	v_pk_add_f32 v[188:189], v[188:189], v[190:191]
	v_pk_add_f32 v[172:173], v[172:173], v[174:175]
	s_nop 0
	v_pk_add_f32 v[172:173], v[188:189], v[172:173]
	ds_bpermute_b32 v174, v194, v172
	ds_bpermute_b32 v175, v194, v173
	s_waitcnt lgkmcnt(0)
	v_pk_add_f32 v[172:173], v[172:173], v[174:175]
	ds_bpermute_b32 v174, v193, v172
	ds_bpermute_b32 v175, v193, v173
	s_and_saveexec_b64 s[2:3], vcc
	s_cbranch_execz .LBB0_341
	v_lshl_or_b32 v186, v199, 5, s4
	s_waitcnt lgkmcnt(0)
	v_pk_add_f32 v[172:173], v[172:173], v[174:175]
	ds_write_b64 v186, v[172:173]
.LBB0_341:
	s_or_b64 exec, exec, s[2:3]
	v_add_u32_e32 v200, 0x90, v192
	v_add_u32_e32 v172, s5, v200
	v_ashrrev_i32_e32 v173, 31, v172
	s_waitcnt lgkmcnt(0)
	v_lshlrev_b64 v[174:175], 12, v[172:173]
	v_lshl_add_u64 v[174:175], s[36:37], 0, v[174:175]
	v_lshl_add_u64 v[174:175], v[160:161], 2, v[174:175]
	s_mov_b32 s2, 0x3fb504f3
	s_waitcnt vmcnt(8)
	v_pk_fma_f32 v[78:79], v[246:247], s[2:3], v[78:79] op_sel_hi:[1,0,1]
	v_pk_fma_f32 v[76:77], v[244:245], s[2:3], v[76:77] op_sel_hi:[1,0,1]
	v_add_f32_e32 v190, v76, v77
	v_add_f32_e32 v202, v78, v79
	v_mul_f32_e32 v205, v76, v76
	v_mul_f32_e32 v215, v77, v77
	v_mul_f32_e32 v221, v78, v78
	v_mul_f32_e32 v223, v79, v79
	v_pk_fma_f32 v[74:75], v[250:251], s[2:3], v[74:75] op_sel_hi:[1,0,1]
	v_pk_fma_f32 v[72:73], v[248:249], s[2:3], v[72:73] op_sel_hi:[1,0,1]
	v_mul_f32_e32 v186, v74, v74
	v_pk_fma_f32 v[224:225], v[74:75], v[74:75], v[186:187] op_sel_hi:[1,1,0]
	v_mul_f32_e32 v191, v72, v72
	v_mul_f32_e32 v203, v73, v73
	v_mov_b32_e32 v204, v72
	v_mov_b32_e32 v214, v73
	v_mov_b32_e32 v220, v74
	v_mov_b32_e32 v222, v75
	v_pk_add_f32 v[204:205], v[204:205], v[214:215]
	v_pk_add_f32 v[214:215], v[220:221], v[222:223]
	v_pk_add_f32 v[190:191], v[190:191], v[202:203]
	v_mov_b32_e32 v224, v177
	v_pk_add_f32 v[204:205], v[204:205], v[214:215]
	v_pk_add_f32 v[190:191], v[190:191], v[224:225]
	v_pk_fma_f32 v[70:71], v[180:181], s[2:3], v[70:71] op_sel_hi:[1,0,1]
	v_pk_fma_f32 v[68:69], v[178:179], s[2:3], v[68:69] op_sel_hi:[1,0,1]
	v_mul_f32_e32 v227, v68, v68
	v_mul_f32_e32 v229, v69, v69
	v_mul_f32_e32 v231, v70, v70
	v_mul_f32_e32 v233, v71, v71
	v_mov_b32_e32 v226, v68
	v_mov_b32_e32 v228, v69
	v_mov_b32_e32 v230, v70
	v_mov_b32_e32 v232, v71
	v_pk_add_f32 v[190:191], v[204:205], v[190:191]
	v_pk_add_f32 v[202:203], v[226:227], v[228:229]
	v_pk_add_f32 v[204:205], v[230:231], v[232:233]
	v_pk_fma_f32 v[66:67], v[184:185], s[2:3], v[66:67] op_sel_hi:[1,0,1]
	v_pk_fma_f32 v[64:65], v[182:183], s[2:3], v[64:65] op_sel_hi:[1,0,1]
	v_mov_b64_e32 v[178:179], 0x100
	v_mov_b64_e32 v[180:181], 0xff
	v_mov_b64_e32 v[182:183], 0x280
	v_mov_b64_e32 v[184:185], 0x27f
	v_mul_f32_e32 v189, v66, v66
	v_mul_f32_e32 v175, v64, v64
	v_mul_f32_e32 v187, v65, v65
	v_mul_f32_e32 v235, v67, v67
	v_mov_b32_e32 v174, v64
	v_mov_b32_e32 v186, v65
	v_mov_b32_e32 v188, v66
	v_mov_b32_e32 v234, v67
	v_pk_add_f32 v[202:203], v[202:203], v[204:205]
	v_pk_add_f32 v[174:175], v[174:175], v[186:187]
	v_pk_add_f32 v[186:187], v[188:189], v[234:235]
	v_pk_add_f32 v[190:191], v[190:191], v[202:203]
	v_pk_add_f32 v[174:175], v[174:175], v[186:187]
	s_nop 0
	v_pk_add_f32 v[174:175], v[190:191], v[174:175]
	ds_bpermute_b32 v186, v194, v174
	ds_bpermute_b32 v187, v194, v175
	s_waitcnt lgkmcnt(0)
	v_pk_add_f32 v[174:175], v[174:175], v[186:187]
	ds_bpermute_b32 v186, v193, v174
	ds_bpermute_b32 v187, v193, v175
	s_and_saveexec_b64 s[2:3], vcc
	s_cbranch_execz .LBB0_343
	v_lshl_or_b32 v188, v200, 5, s4
	s_waitcnt lgkmcnt(0)
	v_pk_add_f32 v[174:175], v[174:175], v[186:187]
	ds_write_b64 v188, v[174:175]
.LBB0_343:
	s_or_b64 exec, exec, s[2:3]
	v_add_u32_e32 v201, 0xa0, v192
	v_add_u32_e32 v174, s5, v201
	v_ashrrev_i32_e32 v175, 31, v174
	s_waitcnt lgkmcnt(0)
	v_lshlrev_b64 v[186:187], 12, v[174:175]
	v_lshl_add_u64 v[186:187], s[36:37], 0, v[186:187]
	v_lshl_add_u64 v[190:191], v[160:161], 2, v[186:187]
	s_mov_b32 s2, 0x3fb504f3
	s_waitcnt vmcnt(4)
	v_pk_fma_f32 v[62:63], v[2:3], s[2:3], v[62:63] op_sel_hi:[1,0,1]
	v_pk_fma_f32 v[60:61], v[0:1], s[2:3], v[60:61] op_sel_hi:[1,0,1]
	v_add_f32_e32 v202, v60, v61
	v_add_f32_e32 v204, v62, v63
	v_mul_f32_e32 v215, v60, v60
	v_mul_f32_e32 v221, v61, v61
	v_mul_f32_e32 v223, v62, v62
	v_mul_f32_e32 v225, v63, v63
	v_pk_fma_f32 v[58:59], v[6:7], s[2:3], v[58:59] op_sel_hi:[1,0,1]
	v_pk_fma_f32 v[56:57], v[4:5], s[2:3], v[56:57] op_sel_hi:[1,0,1]
	v_mul_f32_e32 v186, v58, v58
	v_pk_fma_f32 v[226:227], v[58:59], v[58:59], v[186:187] op_sel_hi:[1,1,0]
	v_mul_f32_e32 v203, v56, v56
	v_mul_f32_e32 v205, v57, v57
	v_mov_b32_e32 v214, v56
	v_mov_b32_e32 v220, v57
	v_mov_b32_e32 v222, v58
	v_mov_b32_e32 v224, v59
	v_pk_add_f32 v[214:215], v[214:215], v[220:221]
	v_pk_add_f32 v[220:221], v[222:223], v[224:225]
	v_pk_add_f32 v[202:203], v[202:203], v[204:205]
	v_mov_b32_e32 v226, v177
	v_pk_add_f32 v[214:215], v[214:215], v[220:221]
	v_pk_add_f32 v[202:203], v[202:203], v[226:227]
	v_pk_fma_f32 v[54:55], v[10:11], s[2:3], v[54:55] op_sel_hi:[1,0,1]
	v_pk_fma_f32 v[52:53], v[8:9], s[2:3], v[52:53] op_sel_hi:[1,0,1]
	v_mul_f32_e32 v229, v52, v52
	v_mul_f32_e32 v231, v53, v53
	v_mul_f32_e32 v233, v54, v54
	v_mul_f32_e32 v235, v55, v55
	v_mov_b32_e32 v228, v52
	v_mov_b32_e32 v230, v53
	v_mov_b32_e32 v232, v54
	v_mov_b32_e32 v234, v55
	v_pk_add_f32 v[202:203], v[214:215], v[202:203]
	v_pk_add_f32 v[204:205], v[228:229], v[230:231]
	v_pk_add_f32 v[214:215], v[232:233], v[234:235]
	v_pk_fma_f32 v[50:51], v[14:15], s[2:3], v[50:51] op_sel_hi:[1,0,1]
	v_pk_fma_f32 v[48:49], v[12:13], s[2:3], v[48:49] op_sel_hi:[1,0,1]
	v_mul_f32_e32 v191, v50, v50
	v_mul_f32_e32 v187, v48, v48
	v_mul_f32_e32 v189, v49, v49
	v_mul_f32_e32 v237, v51, v51
	v_mov_b32_e32 v186, v48
	v_mov_b32_e32 v188, v49
	v_mov_b32_e32 v190, v50
	v_mov_b32_e32 v236, v51
	v_pk_add_f32 v[204:205], v[204:205], v[214:215]
	v_pk_add_f32 v[186:187], v[186:187], v[188:189]
	v_pk_add_f32 v[188:189], v[190:191], v[236:237]
	v_pk_add_f32 v[202:203], v[202:203], v[204:205]
	v_pk_add_f32 v[186:187], v[186:187], v[188:189]
	s_nop 0
	v_pk_add_f32 v[186:187], v[202:203], v[186:187]
	ds_bpermute_b32 v188, v194, v186
	ds_bpermute_b32 v189, v194, v187
	s_waitcnt lgkmcnt(0)
	v_pk_add_f32 v[186:187], v[186:187], v[188:189]
	ds_bpermute_b32 v188, v193, v186
	ds_bpermute_b32 v189, v193, v187
	s_and_saveexec_b64 s[2:3], vcc
	s_cbranch_execz .LBB0_345
	v_lshl_or_b32 v190, v201, 5, s4
	s_waitcnt lgkmcnt(0)
	v_pk_add_f32 v[186:187], v[186:187], v[188:189]
	ds_write_b64 v190, v[186:187]
.LBB0_345:
	s_or_b64 exec, exec, s[2:3]
	v_add_u32_e32 v202, 0xb0, v192
	v_add_u32_e32 v186, s5, v202
	v_ashrrev_i32_e32 v187, 31, v186
	s_waitcnt lgkmcnt(0)
	v_lshlrev_b64 v[188:189], 12, v[186:187]
	v_lshl_add_u64 v[188:189], s[36:37], 0, v[188:189]
	v_lshl_add_u64 v[204:205], v[160:161], 2, v[188:189]
	s_mov_b32 s2, 0x3fb504f3
	s_waitcnt vmcnt(0)
	v_pk_fma_f32 v[46:47], v[18:19], s[2:3], v[46:47] op_sel_hi:[1,0,1]
	v_pk_fma_f32 v[44:45], v[16:17], s[2:3], v[44:45] op_sel_hi:[1,0,1]
	v_add_f32_e32 v214, v44, v45
	v_add_f32_e32 v224, v46, v47
	v_mul_f32_e32 v227, v44, v44
	v_mul_f32_e32 v229, v45, v45
	v_mul_f32_e32 v231, v46, v46
	v_mul_f32_e32 v233, v47, v47
	v_pk_fma_f32 v[42:43], v[22:23], s[2:3], v[42:43] op_sel_hi:[1,0,1]
	v_pk_fma_f32 v[40:41], v[20:21], s[2:3], v[40:41] op_sel_hi:[1,0,1]
	v_mul_f32_e32 v188, v42, v42
	v_pk_fma_f32 v[234:235], v[42:43], v[42:43], v[188:189] op_sel_hi:[1,1,0]
	v_mul_f32_e32 v215, v40, v40
	v_mul_f32_e32 v225, v41, v41
	v_mov_b32_e32 v226, v40
	v_mov_b32_e32 v228, v41
	v_mov_b32_e32 v230, v42
	v_mov_b32_e32 v232, v43
	v_pk_add_f32 v[214:215], v[214:215], v[224:225]
	v_mov_b32_e32 v234, v177
	v_pk_add_f32 v[214:215], v[214:215], v[234:235]
	v_pk_fma_f32 v[38:39], v[26:27], s[2:3], v[38:39] op_sel_hi:[1,0,1]
	v_pk_fma_f32 v[36:37], v[24:25], s[2:3], v[36:37] op_sel_hi:[1,0,1]
	v_pk_fma_f32 v[188:189], v[30:31], s[2:3], v[34:35] op_sel_hi:[1,0,1]
	v_pk_add_f32 v[222:223], v[226:227], v[228:229]
	v_pk_add_f32 v[226:227], v[230:231], v[232:233]
	v_mul_f32_e32 v237, v36, v36
	v_mul_f32_e32 v239, v37, v37
	v_mul_f32_e32 v241, v38, v38
	v_mul_f32_e32 v243, v39, v39
	v_pk_fma_f32 v[190:191], v[28:29], s[2:3], v[32:33] op_sel_hi:[1,0,1]
	s_lshl_b32 s100, s24, 12
	v_readlane_b32 s101, v254, 4
	v_lshl_add_u32 v253, v160, 2, s100
	v_readlane_b32 s100, v254, 3
	s_nop 4
	global_load_dwordx4 v[24:27], v253, s[100:101]
	global_load_dwordx4 v[16:19], v253, s[100:101] offset:64
	global_load_dwordx4 v[8:11], v253, s[100:101] offset:512
	global_load_dwordx4 v[0:3], v253, s[100:101] offset:576
	v_readlane_b32 s100, v254, 5
	v_readlane_b32 s101, v254, 6
	s_nop 4
	global_load_dwordx4 v[28:31], v253, s[100:101]
	global_load_dwordx4 v[20:23], v253, s[100:101] offset:64
	global_load_dwordx4 v[12:15], v253, s[100:101] offset:512
	global_load_dwordx4 v[4:7], v253, s[100:101] offset:576
	v_pk_add_f32 v[222:223], v[222:223], v[226:227]
	v_mov_b32_e32 v236, v36
	v_mov_b32_e32 v238, v37
	v_mov_b32_e32 v240, v38
	v_mov_b32_e32 v242, v39
	v_mul_f32_e32 v33, v190, v190
	v_mul_f32_e32 v35, v191, v191
	v_mul_f32_e32 v205, v188, v188
	v_mul_f32_e32 v221, v189, v189
	v_pk_add_f32 v[214:215], v[222:223], v[214:215]
	v_pk_add_f32 v[222:223], v[236:237], v[238:239]
	v_pk_add_f32 v[224:225], v[240:241], v[242:243]
	v_mov_b32_e32 v32, v190
	v_mov_b32_e32 v34, v191
	v_mov_b32_e32 v204, v188
	v_mov_b32_e32 v220, v189
	v_pk_add_f32 v[222:223], v[222:223], v[224:225]
	v_pk_add_f32 v[32:33], v[32:33], v[34:35]
	v_pk_add_f32 v[34:35], v[204:205], v[220:221]
	v_pk_add_f32 v[214:215], v[214:215], v[222:223]
	v_pk_add_f32 v[32:33], v[32:33], v[34:35]
	s_nop 0
	v_pk_add_f32 v[32:33], v[214:215], v[32:33]
	ds_bpermute_b32 v34, v194, v32
	ds_bpermute_b32 v35, v194, v33
	s_waitcnt lgkmcnt(0)
	v_pk_add_f32 v[32:33], v[32:33], v[34:35]
	ds_bpermute_b32 v34, v193, v32
	ds_bpermute_b32 v35, v193, v33
	s_and_saveexec_b64 s[2:3], vcc
	s_cbranch_execz .LBB0_347
	v_lshl_or_b32 v193, v202, 5, s4
	s_waitcnt lgkmcnt(0)
	v_pk_add_f32 v[32:33], v[32:33], v[34:35]
	ds_write_b64 v193, v[32:33]

.LBB0_361:
	s_or_b64 exec, exec, s[4:5]
	s_barrier
	s_and_saveexec_b64 s[4:5], s[36:37]
	s_cbranch_execz .LBB0_363
	s_lshl_b32 s6, s82, 2
	s_ashr_i32 s7, s6, 31
	v_lshl_add_u64 v[34:35], v[32:33], 3, s[2:3]
	s_lshl_b64 s[2:3], s[6:7], 11
	v_lshl_add_u64 v[194:195], v[34:35], 0, s[2:3]
	global_load_dwordx2 v[220:221], v[194:195], off sc1
	s_or_b32 s2, s6, 1
	s_ashr_i32 s3, s2, 31
	s_lshl_b64 s[2:3], s[2:3], 11
	v_lshlrev_b32_e32 v32, 3, v32
	v_lshl_add_u64 v[194:195], v[34:35], 0, s[2:3]
	global_load_dwordx2 v[222:223], v[194:195], off sc1
	s_or_b32 s2, s6, 2
	s_ashr_i32 s3, s2, 31
	s_lshl_b64 s[2:3], s[2:3], 11
	v_lshl_add_u64 v[194:195], v[34:35], 0, s[2:3]
	s_or_b32 s2, s6, 3
	s_ashr_i32 s3, s2, 31
	s_lshl_b64 s[2:3], s[2:3], 11
	global_load_dwordx2 v[194:195], v[194:195], off sc1
	v_lshl_add_u64 v[34:35], v[34:35], 0, s[2:3]
	global_load_dwordx2 v[34:35], v[34:35], off sc1
	s_mov_b32 s2, 0x3a800000
	s_waitcnt vmcnt(3)
	v_add_f32_e32 v33, 0, v220
	v_add_f32_e32 v176, 0, v221
	s_waitcnt vmcnt(2)
	v_add_f32_e32 v33, v33, v222
	v_add_f32_e32 v176, v176, v223
	s_waitcnt vmcnt(1)
	v_add_f32_e32 v33, v33, v194
	v_add_f32_e32 v176, v176, v195
	s_waitcnt vmcnt(0)
	v_add_f32_e32 v33, v33, v34
	v_mul_f32_e32 v34, 0x3a800000, v33
	v_add_f32_e32 v35, v176, v35
	v_mul_f32_e32 v33, v34, v34
	v_fma_f32 v33, v35, s2, -v33
	v_max_f32_e32 v33, 0, v33
	v_add_f32_e32 v33, 0x3727c5ac, v33
	s_mov_b32 s2, 0x800000
	v_cmp_gt_f32_e32 vcc, s2, v33
	v_mul_f32_e32 v35, 0x4b800000, v33
	s_nop 0
	v_cndmask_b32_e32 v33, v33, v35, vcc
	v_rsq_f32_e32 v33, v33
	s_nop 0
	v_mul_f32_e32 v35, 0x45800000, v33
	v_cndmask_b32_e32 v35, v33, v35, vcc
	ds_write_b64 v32, v[34:35] offset:8192

	.amdhsa_kernel _Z10hybrid_fwd6Paramsii
		.amdhsa_group_segment_fixed_size 131088
		.amdhsa_private_segment_fixed_size 0
		.amdhsa_kernarg_size 368
		.amdhsa_user_sgpr_count 2
		.amdhsa_user_sgpr_dispatch_ptr 0
		.amdhsa_user_sgpr_queue_ptr 0
		.amdhsa_user_sgpr_kernarg_segment_ptr 1
		.amdhsa_user_sgpr_dispatch_id 0
		.amdhsa_user_sgpr_kernarg_preload_length 0
		.amdhsa_user_sgpr_kernarg_preload_offset 0
		.amdhsa_user_sgpr_private_segment_size 0
		.amdhsa_uses_dynamic_stack 0
		.amdhsa_enable_private_segment 0
		.amdhsa_system_sgpr_workgroup_id_x 1
		.amdhsa_system_sgpr_workgroup_id_y 0
		.amdhsa_system_sgpr_workgroup_id_z 0
		.amdhsa_system_sgpr_workgroup_info 0
		.amdhsa_system_vgpr_workitem_id 2
		.amdhsa_next_free_vgpr 256
		.amdhsa_next_free_sgpr 102
		.amdhsa_accum_offset 256
		.amdhsa_reserve_vcc 1
		.amdhsa_float_round_mode_32 0
		.amdhsa_float_round_mode_16_64 0
		.amdhsa_float_denorm_mode_32 3
		.amdhsa_float_denorm_mode_16_64 3
		.amdhsa_dx10_clamp 1
		.amdhsa_ieee_mode 1
		.amdhsa_fp16_overflow 0
		.amdhsa_tg_split 0
		.amdhsa_exception_fp_ieee_invalid_op 0
		.amdhsa_exception_fp_denorm_src 0
		.amdhsa_exception_fp_ieee_div_zero 0
		.amdhsa_exception_fp_ieee_overflow 0
		.amdhsa_exception_fp_ieee_underflow 0
		.amdhsa_exception_fp_ieee_inexact 0
		.amdhsa_exception_int_div_zero 0
	.end_amdhsa_kernel

amdhsa.kernels:
  - .agpr_count:     0
    .args:
      - .offset:         0
        .size:           104
        .value_kind:     by_value
      - .offset:         104
        .size:           4
        .value_kind:     by_value
      - .offset:         108
        .size:           4
        .value_kind:     by_value
      - .offset:         112
        .size:           4
        .value_kind:     hidden_block_count_x
      - .offset:         116
        .size:           4
        .value_kind:     hidden_block_count_y
      - .offset:         120
        .size:           4
        .value_kind:     hidden_block_count_z
      - .offset:         124
        .size:           2
        .value_kind:     hidden_group_size_x
      - .offset:         126
        .size:           2
        .value_kind:     hidden_group_size_y
      - .offset:         128
        .size:           2
        .value_kind:     hidden_group_size_z
      - .offset:         130
        .size:           2
        .value_kind:     hidden_remainder_x
      - .offset:         132
        .size:           2
        .value_kind:     hidden_remainder_y
      - .offset:         134
        .size:           2
        .value_kind:     hidden_remainder_z
      - .offset:         152
        .size:           8
        .value_kind:     hidden_global_offset_x
      - .offset:         160
        .size:           8
        .value_kind:     hidden_global_offset_y
      - .offset:         168
        .size:           8
        .value_kind:     hidden_global_offset_z
      - .offset:         176
        .size:           2
        .value_kind:     hidden_grid_dims
      - .offset:         200
        .size:           8
        .value_kind:     hidden_multigrid_sync_arg
    .group_segment_fixed_size: 131088
    .kernarg_segment_align: 8
    .kernarg_segment_size: 368
    .language:       OpenCL C
    .language_version:
      - 2
      - 0
    .max_flat_workgroup_size: 512
    .name:           _Z10hybrid_fwd6Paramsii
    .private_segment_fixed_size: 0
    .sgpr_count:     108
    .sgpr_spill_count: 119
    .symbol:         _Z10hybrid_fwd6Paramsii.kd
    .uniform_work_group_size: 1
    .uses_dynamic_stack: false
    .vgpr_count:     256
    .vgpr_spill_count: 0
    .wavefront_size: 64
